# s5_fill BtY lag-kernel lanes: two 16-byte kc loads + diagonal load issued before the other lanes' block (one wait per element instead of several)
# speedup vs baseline: 1.0058x; 1.0058x over previous
; DEVI void s5_fill(const Params& p) {
;     ...
;     for (int e = gt; e < 64 * 512 * 80; e += nthr) { const int k8 = (e % 80) * 8, n = (e / 80) & 511, g = e / (80 * 512), t = n >> 4, hh = n & 15; float v[8];
;         if (k8 < 512) { const int s = k8 >> 4, h0 = k8 & 15;
; #pragma unroll
;             for (int j = 0; j < 8; ++j) { float x = 0.f; if (s <= t) { x = kc[(((size_t)g * 32 + (t - s)) * 16 + hh) * 16 + h0 + j]; if (s == t && h0 + j == hh) x += p.in[25][g * 16 + hh]; } v[j] = x; }
;         } else { const int q0 = k8 - 512;
; #pragma unroll
;             for (int j = 0; j < 8; ++j) { const int q = q0 + j, pp = q & 63; const size_t gp = (size_t)g * 64 + pp; const float ar = apow[(gp * 34 + t + 1) * 2], ai = apow[(gp * 34 + t + 1) * 2 + 1];
;                 const float cr = p.in[23][((size_t)g * 16 + hh) * 64 + pp], ci = p.in[24][((size_t)g * 16 + hh) * 64 + pp]; v[j] = (q < 64) ? (cr * ar - ci * ai) : -(cr * ai + ci * ar); } }
.LBB0_1017:
	s_mov_b32 s2, 0x66666667
	v_mul_hi_i32 v0, v20, s2
	s_waitcnt lgkmcnt(0)
	v_ashrrev_i32_e32 v1, 5, v0
	v_lshrrev_b32_e32 v2, 31, v0
	v_add_u32_e32 v30, v1, v2
	s_movk_i32 s2, 0xffb0
	v_mad_u64_u32 v[28:29], s[2:3], v30, s2, v[20:21]
	v_ashrrev_i32_e32 v0, 14, v0
	s_movk_i32 s2, 0xfd80
	v_add_u32_e32 v24, v0, v2
	v_mad_u64_u32 v[22:23], s[2:3], v30, s2, v[18:19]
	v_bfe_u32 v26, v30, 4, 5
	v_and_b32_e32 v16, 15, v30
	v_cmp_lt_i32_e32 vcc, 63, v28
	v_ashrrev_i32_e32 v25, 31, v24
	s_mov_b64 s[100:101], exec
	s_mov_b64 s[14:15], 0
	s_andn2_b64 exec, exec, vcc
	s_cbranch_execz .Lbtya_noA
	v_ashrrev_i32_e32 v2, 1, v28
	v_readlane_b32 s2, v252, 40
	v_readlane_b32 s3, v252, 41
	v_sub_u32_e32 v8, v26, v2
	v_lshlrev_b64 v[10:11], 9, v[24:25]
	v_lshl_add_u64 v[0:1], v[8:9], 4, v[10:11]
	v_or_b32_e32 v0, v0, v16
	v_and_b32_e32 v17, 8, v22
	v_lshlrev_b64 v[0:1], 6, v[0:1]
	v_lshlrev_b32_e32 v8, 2, v17
	v_readlane_b32 s38, v251, 42
	v_readlane_b32 s39, v251, 43
	v_lshl_add_u64 v[0:1], s[2:3], 0, v[0:1]
	v_lshl_add_u64 v[12:13], v[0:1], 0, v[8:9]
	v_lshl_or_b32 v0, v24, 4, v16
	v_ashrrev_i32_e32 v1, 31, v0
	v_cmp_ge_i32_e32 vcc, v26, v2
	v_cmp_eq_u32_e64 s[4:5], v26, v2
	v_lshl_add_u64 v[14:15], v[0:1], 2, s[38:39]
	v_and_b32_e32 v8, 8, v16
	v_cmp_eq_u32_e64 s[14:15], v8, v17
	v_mov_b32_e32 v0, 0
	v_mov_b32_e32 v1, 0
	v_mov_b32_e32 v2, 0
	v_mov_b32_e32 v3, 0
	v_mov_b32_e32 v4, 0
	v_mov_b32_e32 v5, 0
	v_mov_b32_e32 v6, 0
	v_mov_b32_e32 v7, 0
	s_and_b64 s[14:15], s[14:15], s[4:5]
	s_and_b64 s[14:15], s[14:15], exec
	s_and_b64 exec, exec, vcc
	global_load_dwordx4 v[0:3], v[12:13], off
	global_load_dwordx4 v[4:7], v[12:13], off offset:16
	s_mov_b64 exec, s[14:15]
	global_load_dword v32, v[14:15], off
.Lbtya_noA:
	s_mov_b64 exec, s[100:101]
	v_cmp_lt_i32_e32 vcc, 63, v28
	s_and_saveexec_b64 s[2:3], vcc
	s_xor_b64 s[2:3], exec, s[2:3]
	s_cbranch_execz .LBB0_1019
	v_lshlrev_b64 v[0:1], 10, v[24:25]
	v_lshlrev_b32_e32 v4, 6, v16
	v_and_b32_e32 v5, 56, v22
	v_lshl_or_b32 v8, v24, 6, v5
	v_or3_b32 v0, v0, v4, v5
	v_readlane_b32 s36, v252, 14
	v_lshlrev_b64 v[4:5], 2, v[0:1]
	v_readlane_b32 s37, v252, 15
	v_readlane_b32 s38, v252, 16
	v_readlane_b32 s39, v252, 17
	v_readlane_b32 s40, v252, 18
	v_readlane_b32 s41, v252, 19
	v_readlane_b32 s42, v252, 20
	v_readlane_b32 s43, v252, 21
	v_readlane_b32 s44, v252, 22
	v_readlane_b32 s45, v252, 23
	v_readlane_b32 s46, v252, 24
	v_readlane_b32 s47, v252, 25
	v_readlane_b32 s48, v252, 26
	v_readlane_b32 s49, v252, 27
	v_readlane_b32 s50, v252, 28
	v_readlane_b32 s51, v252, 29
	s_movk_i32 s4, 0x48
	v_or_b32_e32 v23, 1, v8
	v_mov_b32_e32 v27, v9
	v_mul_hi_i32_i24_e32 v3, 34, v8
	v_mul_i32_i24_e32 v2, 34, v8
	v_lshl_add_u64 v[0:1], s[50:51], 0, v[4:5]
	v_readlane_b32 s36, v251, 40
	v_cmp_gt_u32_e32 vcc, s4, v28
	v_mul_hi_i32_i24_e32 v29, 34, v23
	v_mul_i32_i24_e32 v28, 34, v23
	v_lshl_add_u64 v[2:3], v[2:3], 0, v[26:27]
	v_readlane_b32 s37, v251, 41
	v_lshl_add_u64 v[28:29], v[28:29], 0, v[26:27]
	v_lshl_add_u64 v[32:33], v[2:3], 3, s[56:57]
	v_lshl_add_u64 v[4:5], s[36:37], 0, v[4:5]
	v_lshl_add_u64 v[28:29], v[28:29], 3, s[56:57]
	global_load_dwordx4 v[10:13], v[0:1], off offset:16
	s_nop 0
	global_load_dwordx4 v[0:3], v[0:1], off
	s_nop 0
	global_load_dwordx4 v[14:17], v[4:5], off offset:16
	s_nop 0
	global_load_dwordx4 v[4:7], v[4:5], off
	s_nop 0
	global_load_dwordx2 v[32:33], v[32:33], off offset:8
	s_nop 0
	global_load_dwordx2 v[28:29], v[28:29], off offset:8
	v_or_b32_e32 v60, 2, v8
	v_mul_hi_i32_i24_e32 v61, 34, v60
	v_mul_i32_i24_e32 v60, 34, v60
	v_lshl_add_u64 v[60:61], v[60:61], 0, v[26:27]
	v_lshl_add_u64 v[60:61], v[60:61], 3, s[56:57]
	global_load_dwordx2 v[60:61], v[60:61], off offset:8
	v_or_b32_e32 v62, 3, v8
	v_mul_hi_i32_i24_e32 v63, 34, v62
	v_mul_i32_i24_e32 v62, 34, v62
	v_lshl_add_u64 v[62:63], v[62:63], 0, v[26:27]
	v_lshl_add_u64 v[62:63], v[62:63], 3, s[56:57]
	global_load_dwordx2 v[62:63], v[62:63], off offset:8
	v_or_b32_e32 v64, 4, v8
	v_mul_hi_i32_i24_e32 v65, 34, v64
	v_mul_i32_i24_e32 v64, 34, v64
	v_lshl_add_u64 v[64:65], v[64:65], 0, v[26:27]
	v_lshl_add_u64 v[64:65], v[64:65], 3, s[56:57]
	global_load_dwordx2 v[64:65], v[64:65], off offset:8
	v_or_b32_e32 v66, 5, v8
	v_mul_hi_i32_i24_e32 v67, 34, v66
	v_mul_i32_i24_e32 v66, 34, v66
	v_lshl_add_u64 v[66:67], v[66:67], 0, v[26:27]
	v_lshl_add_u64 v[66:67], v[66:67], 3, s[56:57]
	global_load_dwordx2 v[66:67], v[66:67], off offset:8
	v_or_b32_e32 v68, 6, v8
	v_mul_hi_i32_i24_e32 v69, 34, v68
	v_mul_i32_i24_e32 v68, 34, v68
	v_lshl_add_u64 v[68:69], v[68:69], 0, v[26:27]
	v_lshl_add_u64 v[68:69], v[68:69], 3, s[56:57]
	global_load_dwordx2 v[68:69], v[68:69], off offset:8
	v_or_b32_e32 v70, 7, v8
	v_mul_hi_i32_i24_e32 v71, 34, v70
	v_mul_i32_i24_e32 v70, 34, v70
	v_lshl_add_u64 v[70:71], v[70:71], 0, v[26:27]
	v_lshl_add_u64 v[70:71], v[70:71], 3, s[56:57]
	global_load_dwordx2 v[70:71], v[70:71], off offset:8
	v_readlane_b32 s40, v251, 44
	v_readlane_b32 s38, v251, 42
	v_readlane_b32 s39, v251, 43
	v_readlane_b32 s41, v251, 45
	v_readlane_b32 s42, v251, 46
	v_readlane_b32 s43, v251, 47
	v_readlane_b32 s44, v251, 48
	v_readlane_b32 s45, v251, 49
	v_readlane_b32 s46, v251, 50
	v_readlane_b32 s47, v251, 51
	v_readlane_b32 s48, v251, 52
	v_readlane_b32 s49, v251, 53
	v_readlane_b32 s50, v251, 54
	v_readlane_b32 s51, v251, 55
	v_readlane_b32 s40, v254, 1
	s_waitcnt vmcnt(7)
; DEVI void s5_fill(const Params& p) {
;     ...
;         if (k8 < 512) { const int s = k8 >> 4, h0 = k8 & 15;
; #pragma unroll
;             for (int j = 0; j < 8; ++j) { float x = 0.f; if (s <= t) { x = kc[(((size_t)g * 32 + (t - s)) * 16 + hh) * 16 + h0 + j]; if (s == t && h0 + j == hh) x += p.in[25][g * 16 + hh]; } v[j] = x; }
;         } else { const int q0 = k8 - 512;
; #pragma unroll
;             for (int j = 0; j < 8; ++j) { const int q = q0 + j, pp = q & 63; const size_t gp = (size_t)g * 64 + pp; const float ar = apow[(gp * 34 + t + 1) * 2], ai = apow[(gp * 34 + t + 1) * 2 + 1];
;                 const float cr = p.in[23][((size_t)g * 16 + hh) * 64 + pp], ci = p.in[24][((size_t)g * 16 + hh) * 64 + pp]; v[j] = (q < 64) ? (cr * ar - ci * ai) : -(cr * ai + ci * ar); } }
	v_mov_b32_e32 v34, v32
	s_waitcnt vmcnt(6)
	v_mov_b32_e32 v35, v28
	v_mov_b32_e32 v28, v33
	v_pk_mul_f32 v[32:33], v[28:29], v[4:5]
	v_pk_mul_f32 v[4:5], v[34:35], v[4:5]
	v_pk_fma_f32 v[32:33], v[34:35], v[0:1], v[32:33] neg_lo:[0,0,1] neg_hi:[0,0,1]
	v_pk_fma_f32 v[0:1], v[28:29], v[0:1], v[4:5]
	v_cndmask_b32_e64 v1, -v1, v33, vcc
	v_cndmask_b32_e64 v0, -v0, v32, vcc
	s_waitcnt vmcnt(5)
	v_mov_b32_e32 v4, v60
	v_mov_b32_e32 v5, v61
	v_mov_b32_e32 v32, v4
	s_waitcnt vmcnt(4)
	v_mov_b32_e32 v28, v62
	v_mov_b32_e32 v29, v63
	v_mov_b32_e32 v33, v28
	v_mov_b32_e32 v28, v5
	v_pk_mul_f32 v[4:5], v[28:29], v[6:7]
	v_pk_mul_f32 v[6:7], v[32:33], v[6:7]
	v_pk_fma_f32 v[4:5], v[32:33], v[2:3], v[4:5] neg_lo:[0,0,1] neg_hi:[0,0,1]
	v_pk_fma_f32 v[2:3], v[28:29], v[2:3], v[6:7]
	v_cndmask_b32_e64 v2, -v2, v4, vcc
	v_cndmask_b32_e64 v3, -v3, v5, vcc
	s_waitcnt vmcnt(3)
	v_mov_b32_e32 v4, v64
	v_mov_b32_e32 v5, v65
	v_mov_b32_e32 v28, v4
	s_waitcnt vmcnt(2)
	v_mov_b32_e32 v6, v66
	v_mov_b32_e32 v7, v67
	v_mov_b32_e32 v29, v6
	v_mov_b32_e32 v6, v5
	v_pk_mul_f32 v[4:5], v[6:7], v[14:15]
	v_pk_mul_f32 v[14:15], v[28:29], v[14:15]
	v_pk_fma_f32 v[4:5], v[28:29], v[10:11], v[4:5] neg_lo:[0,0,1] neg_hi:[0,0,1]
	v_pk_fma_f32 v[6:7], v[6:7], v[10:11], v[14:15]
	v_mov_b32_e32 v10, v12
	v_cndmask_b32_e64 v4, -v6, v4, vcc
	v_cndmask_b32_e64 v5, -v7, v5, vcc
	v_mov_b32_e32 v11, v16
	s_waitcnt vmcnt(1)
	v_mov_b32_e32 v6, v68
	v_mov_b32_e32 v7, v69
	v_pk_mul_f32 v[10:11], v[6:7], v[10:11]
	s_nop 0
	v_sub_f32_e32 v14, v10, v11
	v_mov_b32_e32 v10, v16
	v_mov_b32_e32 v11, v12
	v_pk_mul_f32 v[6:7], v[6:7], v[10:11]
	v_mov_b32_e32 v16, v13
	v_add_f32_e32 v6, v7, v6
	v_mov_b32_e32 v12, v17
	v_cndmask_b32_e64 v6, -v6, v14, vcc
	s_waitcnt vmcnt(0)
	v_mov_b32_e32 v10, v70
	v_mov_b32_e32 v11, v71
	v_pk_mul_f32 v[14:15], v[10:11], v[16:17]
	v_pk_mul_f32 v[10:11], v[10:11], v[12:13]
	v_sub_f32_e32 v7, v14, v15
	v_add_f32_e32 v8, v11, v10
	v_cndmask_b32_e64 v7, -v8, v7, vcc
	v_lshlrev_b64 v[10:11], 9, v[24:25]
.LBB0_1019:
	s_andn2_saveexec_b64 s[10:11], s[2:3]
	s_cbranch_execz .LBB0_1016
	v_readlane_b32 s36, v251, 40
	v_readlane_b32 s38, v251, 42
	v_readlane_b32 s39, v251, 43
	v_readlane_b32 s37, v251, 41
	v_readlane_b32 s40, v251, 44
	v_readlane_b32 s41, v251, 45
	v_readlane_b32 s42, v251, 46
	v_readlane_b32 s43, v251, 47
	v_readlane_b32 s44, v251, 48
	v_readlane_b32 s45, v251, 49
	v_readlane_b32 s46, v251, 50
	v_readlane_b32 s47, v251, 51
	v_readlane_b32 s48, v251, 52
	v_readlane_b32 s49, v251, 53
	v_readlane_b32 s50, v251, 54
	v_readlane_b32 s51, v251, 55
	v_readlane_b32 s40, v254, 1
	s_waitcnt vmcnt(0)
	s_and_saveexec_b64 s[4:5], s[14:15]
	s_cbranch_execz .Lbtya_nod
	v_and_b32_e32 v8, 7, v16
	v_cmp_eq_u32_e32 vcc, 0, v8
	v_add_f32_e32 v33, v0, v32
	s_nop 1
	v_cndmask_b32_e32 v0, v0, v33, vcc
	v_cmp_eq_u32_e32 vcc, 1, v8
	v_add_f32_e32 v33, v1, v32
	s_nop 1
	v_cndmask_b32_e32 v1, v1, v33, vcc
	v_cmp_eq_u32_e32 vcc, 2, v8
	v_add_f32_e32 v33, v2, v32
	s_nop 1
	v_cndmask_b32_e32 v2, v2, v33, vcc
	v_cmp_eq_u32_e32 vcc, 3, v8
	v_add_f32_e32 v33, v3, v32
	s_nop 1
	v_cndmask_b32_e32 v3, v3, v33, vcc
	v_cmp_eq_u32_e32 vcc, 4, v8
	v_add_f32_e32 v33, v4, v32
	s_nop 1
	v_cndmask_b32_e32 v4, v4, v33, vcc
	v_cmp_eq_u32_e32 vcc, 5, v8
	v_add_f32_e32 v33, v5, v32
	s_nop 1
	v_cndmask_b32_e32 v5, v5, v33, vcc
	v_cmp_eq_u32_e32 vcc, 6, v8
	v_add_f32_e32 v33, v6, v32
	s_nop 1
	v_cndmask_b32_e32 v6, v6, v33, vcc
	v_cmp_eq_u32_e32 vcc, 7, v8
	v_add_f32_e32 v33, v7, v32
	s_nop 1
	v_cndmask_b32_e32 v7, v7, v33, vcc
.Lbtya_nod:
	s_or_b64 exec, exec, s[4:5]
	s_branch .LBB0_1016
